# RSCAN: one workgroup barrier per scan step - next P tile published before the S-exchange barrier, S exchange buffer double-buffered by step parity
# speedup vs baseline: 1.0036x; 1.0036x over previous
; #define LAS __attribute__((address_space(3)))
; __device__ __forceinline__ void rk_scan(LAS unsigned char* lds, unsigned char* ws, int bid, int wid_s) {
;     ...
;     if (q == 0) { *(LAS f32x4*)(SX + i * 68 + 8 * wid) = r0; *(LAS f32x4*)(SX + i * 68 + 8 * wid + 4) = r1;
;       *(f32x4*)(Bg + (size_t)c * 4096 + brow) = r0; *(f32x4*)(Bg + (size_t)c * 4096 + brow + 4) = r1; }
;     asm volatile("s_waitcnt lgkmcnt(0)" ::: "memory"); __builtin_amdgcn_s_barrier(); asm volatile("" ::: "memory");
; #pragma unroll
;     for (int j = 0; j < 4; ++j) { const f32x4 v = *(const LAS f32x4*)(SX + i * 68 + q * 16 + 4 * j); S[2 * j] = (f32x2){v.x, v.y}; S[2 * j + 1] = (f32x2){v.z, v.w}; }
;     if (c + 1 < RK_NC) { LAS float* pn = PL + ((c + 1) & 1) * 4096; *(LAS f32x4*)(pn + tid * 8) = p0; *(LAS f32x4*)(pn + tid * 8 + 4) = p1; }
;     asm volatile("s_waitcnt lgkmcnt(0)" ::: "memory"); __builtin_amdgcn_s_barrier(); asm volatile("" ::: "memory");
.LBB0_33:
	s_or_b64 exec, exec, s[6:7]
	s_and_b32 s6, s9, 0x1000
	v_lshl_add_u32 v0, s6, 2, v57
	s_waitcnt vmcnt(6)
	ds_write_b128 v0, v[130:133]
	ds_write_b128 v0, v[134:137] offset:16
	s_waitcnt lgkmcnt(0)
	s_barrier
	ds_read_b128 v[38:41], v59 offset:32768
	ds_read_b128 v[26:29], v59 offset:32784
	ds_read_b128 v[18:21], v59 offset:32800
	ds_read_b128 v[22:25], v59 offset:32816
	s_add_u32 s4, s4, 0x4000
	s_addc_u32 s5, s5, 0
	s_addk_i32 s9, 0x1000
	v_mov_b64_e32 v[12:13], v[140:141]
	v_mov_b64_e32 v[16:17], v[144:145]
	s_cmp_lg_u32 s4, 0x1fc000
	v_mov_b64_e32 v[10:11], v[138:139]
	v_mov_b64_e32 v[14:15], v[142:143]
	s_waitcnt lgkmcnt(3)
	v_mov_b32_e32 v64, v39
	v_mov_b32_e32 v62, v41
	s_waitcnt lgkmcnt(2)
	v_mov_b32_e32 v58, v27
	v_mov_b32_e32 v54, v29
	s_waitcnt lgkmcnt(1)
	v_mov_b32_e32 v0, v19
	v_mov_b32_e32 v52, v21
	s_waitcnt lgkmcnt(0)
	v_mov_b32_e32 v60, v23
	v_mov_b32_e32 v56, v25
	s_cbranch_scc1 .Lrs_odd_top
	s_waitcnt vmcnt(0)
	s_nop 0
	v_mov_b64_e32 v[2:3], v[138:139]
	v_mov_b64_e32 v[4:5], v[140:141]
	v_mov_b64_e32 v[6:7], v[142:143]
	v_mov_b64_e32 v[8:9], v[144:145]
	s_branch .LBB0_36

; #define LAS __attribute__((address_space(3)))
; __device__ __forceinline__ void rk_scan(LAS unsigned char* lds, unsigned char* ws, int bid, int wid_s) {
;     ...
;   for (int c = 0; c < RK_NC; ++c) {
;     const LAS float* pl = PL + (c & 1) * 4096 + 8 * wid + q * 16 * 64;
;     const f32x4 b0 = bn0, b1 = bn1;
;     if (c + 1 < RK_NC) { p0 = *(const f32x4*)(Pg + (size_t)(c + 1) * 4096 + tid * 8); p1 = *(const f32x4*)(Pg + (size_t)(c + 1) * 4096 + tid * 8 + 4);
;       bn0 = *(const f32x4*)(Bg + (size_t)(c + 1) * 4096 + brow); bn1 = *(const f32x4*)(Bg + (size_t)(c + 1) * 4096 + brow + 4); }
;     f32x2 o0 = (f32x2){zf, zf}, o1 = o0, o2 = o0, o3 = o0;
;     f32x4 PA[2][4], PB[2][4];
; #pragma unroll
;     for (int j = 0; j < 4; ++j) { PA[0][j] = *(const LAS f32x4*)(pl + j * 64); PB[0][j] = *(const LAS f32x4*)(pl + j * 64 + 4); }
; #pragma unroll
;     for (int g = 0; g < 4; ++g) {
;       if (g + 1 < 4) {
; #pragma unroll
;         for (int j = 0; j < 4; ++j) { PA[(g + 1) & 1][j] = *(const LAS f32x4*)(pl + (4 * (g + 1) + j) * 64); PB[(g + 1) & 1][j] = *(const LAS f32x4*)(pl + (4 * (g + 1) + j) * 64 + 4); }
;       }
; #pragma unroll
;       for (int j = 0; j < 4; ++j) { const int k = 4 * g + j; const f32x4 pa = PA[g & 1][j], pb = PB[g & 1][j];
;         const float s = (k & 1) ? S[k >> 1].y : S[k >> 1].x; const f32x2 s2 = (f32x2){s, s};
;         o0 += s2 * (f32x2){pa.x, pa.y}; o1 += s2 * (f32x2){pa.z, pa.w}; o2 += s2 * (f32x2){pb.x, pb.y}; o3 += s2 * (f32x2){pb.z, pb.w}; }
;     ...
;     if (q == 0) { *(LAS f32x4*)(SX + i * 68 + 8 * wid) = r0; *(LAS f32x4*)(SX + i * 68 + 8 * wid + 4) = r1;
;       *(f32x4*)(Bg + (size_t)c * 4096 + brow) = r0; *(f32x4*)(Bg + (size_t)c * 4096 + brow + 4) = r1; }
;     asm volatile("s_waitcnt lgkmcnt(0)" ::: "memory"); __builtin_amdgcn_s_barrier(); asm volatile("" ::: "memory");
; #pragma unroll
;     for (int j = 0; j < 4; ++j) { const f32x4 v = *(const LAS f32x4*)(SX + i * 68 + q * 16 + 4 * j); S[2 * j] = (f32x2){v.x, v.y}; S[2 * j + 1] = (f32x2){v.z, v.w}; }
;     if (c + 1 < RK_NC) { LAS float* pn = PL + ((c + 1) & 1) * 4096; *(LAS f32x4*)(pn + tid * 8) = p0; *(LAS f32x4*)(pn + tid * 8 + 4) = p1; }
;     asm volatile("s_waitcnt lgkmcnt(0)" ::: "memory"); __builtin_amdgcn_s_barrier(); asm volatile("" ::: "memory");
.Lrs_odd_bot:
	s_or_b64 exec, exec, s[6:7]
	s_and_b32 s6, s9, 0x1000
	v_lshl_add_u32 v0, s6, 2, v57
	s_waitcnt vmcnt(6)
	ds_write_b128 v0, v[34:37]
	ds_write_b128 v0, v[30:33] offset:16
	s_waitcnt lgkmcnt(0)
	s_barrier
	ds_read_b128 v[38:41], v59 offset:40960
	ds_read_b128 v[26:29], v59 offset:40976
	ds_read_b128 v[18:21], v59 offset:40992
	ds_read_b128 v[22:25], v59 offset:41008
	s_add_u32 s4, s4, 0x4000
	s_addc_u32 s5, s5, 0
	s_addk_i32 s9, 0x1000
	v_mov_b64_e32 v[12:13], v[4:5]
	v_mov_b64_e32 v[16:17], v[8:9]
	s_cmp_lg_u32 s4, 0x1fc000
	v_mov_b64_e32 v[10:11], v[2:3]
	v_mov_b64_e32 v[14:15], v[6:7]
	s_waitcnt lgkmcnt(3)
	v_mov_b32_e32 v64, v39
	v_mov_b32_e32 v62, v41
	s_waitcnt lgkmcnt(2)
	v_mov_b32_e32 v58, v27
	v_mov_b32_e32 v54, v29
	s_waitcnt lgkmcnt(1)
	v_mov_b32_e32 v0, v19
	v_mov_b32_e32 v52, v21
	s_waitcnt lgkmcnt(0)
	v_mov_b32_e32 v60, v23
	v_mov_b32_e32 v56, v25
	s_branch .LBB0_34
.Lrs_odd_top:
	s_add_i32 s6, s9, 0xfffff000
	s_and_b32 s6, s6, 0x1000
	v_lshl_add_u32 v19, s6, 2, v55
	v_lshl_add_u64 v[50:51], v[48:49], 0, s[4:5]
	s_mov_b64 s[6:7], 0xbe08000
	v_lshl_add_u64 v[150:151], v[50:51], 0, s[6:7]
	v_lshl_add_u64 v[146:147], v[46:47], 0, s[4:5]
	s_mov_b64 s[6:7], 0xde08000
	v_lshl_add_u64 v[152:153], v[146:147], 0, s[6:7]
	global_load_dwordx4 v[130:133], v[152:153], off
	global_load_dwordx4 v[138:141], v[150:151], off
	global_load_dwordx4 v[134:137], v[152:153], off offset:16
	global_load_dwordx4 v[142:145], v[150:151], off offset:16
	ds_read_b128 v[66:69], v19
	ds_read_b128 v[70:73], v19 offset:16
	ds_read_b128 v[74:77], v19 offset:256
	ds_read_b128 v[78:81], v19 offset:272
	ds_read_b128 v[82:85], v19 offset:512
	ds_read_b128 v[86:89], v19 offset:528
	ds_read_b128 v[90:93], v19 offset:768
	ds_read_b128 v[94:97], v19 offset:784
	ds_read_b128 v[98:101], v19 offset:1024
	ds_read_b128 v[102:105], v19 offset:1040
	ds_read_b128 v[106:109], v19 offset:1280
	ds_read_b128 v[110:113], v19 offset:1296
	ds_read_b128 v[114:117], v19 offset:1536
	ds_read_b128 v[118:121], v19 offset:1552
	ds_read_b128 v[122:125], v19 offset:1792
	ds_read_b128 v[126:129], v19 offset:1808
	s_waitcnt lgkmcnt(14)
	v_pk_fma_f32 v[66:67], v[38:39], v[66:67], v[44:45] op_sel_hi:[0,1,1]
	v_pk_fma_f32 v[68:69], v[38:39], v[68:69], v[44:45] op_sel_hi:[0,1,1]
	v_pk_fma_f32 v[70:71], v[38:39], v[70:71], v[44:45] op_sel_hi:[0,1,1]
	v_pk_fma_f32 v[38:39], v[38:39], v[72:73], v[44:45] op_sel_hi:[0,1,1]
	s_waitcnt lgkmcnt(13)
	v_pk_fma_f32 v[66:67], v[64:65], v[74:75], v[66:67] op_sel_hi:[0,1,1]
	v_pk_fma_f32 v[68:69], v[64:65], v[76:77], v[68:69] op_sel_hi:[0,1,1]
	s_waitcnt lgkmcnt(12)
	v_pk_fma_f32 v[70:71], v[64:65], v[78:79], v[70:71] op_sel_hi:[0,1,1]
	v_pk_fma_f32 v[38:39], v[64:65], v[80:81], v[38:39] op_sel_hi:[0,1,1]
	s_waitcnt lgkmcnt(11)
	v_pk_fma_f32 v[64:65], v[40:41], v[82:83], v[66:67] op_sel_hi:[0,1,1]
	v_pk_fma_f32 v[66:67], v[40:41], v[84:85], v[68:69] op_sel_hi:[0,1,1]
	s_waitcnt lgkmcnt(10)
	v_pk_fma_f32 v[68:69], v[40:41], v[86:87], v[70:71] op_sel_hi:[0,1,1]
	v_pk_fma_f32 v[38:39], v[40:41], v[88:89], v[38:39] op_sel_hi:[0,1,1]
	s_waitcnt lgkmcnt(9)
	v_pk_fma_f32 v[90:91], v[62:63], v[90:91], v[64:65] op_sel_hi:[0,1,1]
	v_pk_fma_f32 v[92:93], v[62:63], v[92:93], v[66:67] op_sel_hi:[0,1,1]
	s_waitcnt lgkmcnt(8)
	v_pk_fma_f32 v[94:95], v[62:63], v[94:95], v[68:69] op_sel_hi:[0,1,1]
	v_pk_fma_f32 v[96:97], v[62:63], v[96:97], v[38:39] op_sel_hi:[0,1,1]
	s_waitcnt lgkmcnt(7)
	v_pk_fma_f32 v[90:91], v[26:27], v[98:99], v[90:91] op_sel_hi:[0,1,1]
	v_pk_fma_f32 v[92:93], v[26:27], v[100:101], v[92:93] op_sel_hi:[0,1,1]
	s_waitcnt lgkmcnt(6)
	v_pk_fma_f32 v[94:95], v[26:27], v[102:103], v[94:95] op_sel_hi:[0,1,1]
	v_pk_fma_f32 v[26:27], v[26:27], v[104:105], v[96:97] op_sel_hi:[0,1,1]
	s_waitcnt lgkmcnt(5)
	v_pk_fma_f32 v[90:91], v[58:59], v[106:107], v[90:91] op_sel_hi:[0,1,1]
	v_pk_fma_f32 v[92:93], v[58:59], v[108:109], v[92:93] op_sel_hi:[0,1,1]
	s_waitcnt lgkmcnt(4)
	v_pk_fma_f32 v[94:95], v[58:59], v[110:111], v[94:95] op_sel_hi:[0,1,1]
	v_pk_fma_f32 v[26:27], v[58:59], v[112:113], v[26:27] op_sel_hi:[0,1,1]
	ds_read_b128 v[38:41], v19 offset:2048
	ds_read_b128 v[62:65], v19 offset:2064
	ds_read_b128 v[66:69], v19 offset:2304
	ds_read_b128 v[70:73], v19 offset:2320
	ds_read_b128 v[74:77], v19 offset:2560
	ds_read_b128 v[78:81], v19 offset:2576
	ds_read_b128 v[82:85], v19 offset:2816
	ds_read_b128 v[86:89], v19 offset:2832
	s_waitcnt lgkmcnt(11)
	v_pk_fma_f32 v[90:91], v[28:29], v[114:115], v[90:91] op_sel_hi:[0,1,1]
	v_pk_fma_f32 v[92:93], v[28:29], v[116:117], v[92:93] op_sel_hi:[0,1,1]
	s_waitcnt lgkmcnt(10)
	v_pk_fma_f32 v[94:95], v[28:29], v[118:119], v[94:95] op_sel_hi:[0,1,1]
	v_pk_fma_f32 v[26:27], v[28:29], v[120:121], v[26:27] op_sel_hi:[0,1,1]
	s_waitcnt lgkmcnt(9)
	v_pk_fma_f32 v[118:119], v[54:55], v[122:123], v[90:91] op_sel_hi:[0,1,1]
	v_pk_fma_f32 v[120:121], v[54:55], v[124:125], v[92:93] op_sel_hi:[0,1,1]
	s_waitcnt lgkmcnt(8)
	v_pk_fma_f32 v[122:123], v[54:55], v[126:127], v[94:95] op_sel_hi:[0,1,1]
	v_pk_fma_f32 v[124:125], v[54:55], v[128:129], v[26:27] op_sel_hi:[0,1,1]
	ds_read_b128 v[26:29], v19 offset:3072
	ds_read_b128 v[90:93], v19 offset:3088
	ds_read_b128 v[94:97], v19 offset:3328
	ds_read_b128 v[98:101], v19 offset:3344
	ds_read_b128 v[102:105], v19 offset:3584
	ds_read_b128 v[106:109], v19 offset:3600
	ds_read_b128 v[110:113], v19 offset:3840
	ds_read_b128 v[114:117], v19 offset:3856
	s_waitcnt lgkmcnt(14)
; #define LAS __attribute__((address_space(3)))
; __device__ __forceinline__ void rk_scan(LAS unsigned char* lds, unsigned char* ws, int bid, int wid_s) {
;     ...
;       for (int j = 0; j < 4; ++j) { const int k = 4 * g + j; const f32x4 pa = PA[g & 1][j], pb = PB[g & 1][j];
;         const float s = (k & 1) ? S[k >> 1].y : S[k >> 1].x; const f32x2 s2 = (f32x2){s, s};
;         o0 += s2 * (f32x2){pa.x, pa.y}; o1 += s2 * (f32x2){pa.z, pa.w}; o2 += s2 * (f32x2){pb.x, pb.y}; o3 += s2 * (f32x2){pb.z, pb.w}; }
;       asm volatile("" ::: "memory");
;     }
;     float ov[8] = {o0.x, o0.y, o1.x, o1.y, o2.x, o2.y, o3.x, o3.y};
; #pragma unroll
;     for (int j = 0; j < 8; ++j) { float v = ov[j];
;       v += __builtin_bit_cast(float, __builtin_amdgcn_update_dpp(0, __builtin_bit_cast(int, v), 0xB1, 0xf, 0xf, false));
;       v += __builtin_bit_cast(float, __builtin_amdgcn_update_dpp(0, __builtin_bit_cast(int, v), 0x4E, 0xf, 0xf, false));
;       ov[j] = v; }
;     const f32x4 r0 = (f32x4){ov[0] + b0.x, ov[1] + b0.y, ov[2] + b0.z, ov[3] + b0.w}, r1 = (f32x4){ov[4] + b1.x, ov[5] + b1.y, ov[6] + b1.z, ov[7] + b1.w};
;     if (q == 0) { *(LAS f32x4*)(SX + i * 68 + 8 * wid) = r0; *(LAS f32x4*)(SX + i * 68 + 8 * wid + 4) = r1;
;       *(f32x4*)(Bg + (size_t)c * 4096 + brow) = r0; *(f32x4*)(Bg + (size_t)c * 4096 + brow + 4) = r1; }
	v_pk_fma_f32 v[64:65], v[18:19], v[64:65], v[124:125] op_sel_hi:[0,1,1]
	v_pk_fma_f32 v[62:63], v[18:19], v[62:63], v[122:123] op_sel_hi:[0,1,1]
	v_pk_fma_f32 v[40:41], v[18:19], v[40:41], v[120:121] op_sel_hi:[0,1,1]
	v_pk_fma_f32 v[18:19], v[18:19], v[38:39], v[118:119] op_sel_hi:[0,1,1]
	s_waitcnt lgkmcnt(12)
	v_pk_fma_f32 v[64:65], v[0:1], v[72:73], v[64:65] op_sel_hi:[0,1,1]
	v_pk_fma_f32 v[62:63], v[0:1], v[70:71], v[62:63] op_sel_hi:[0,1,1]
	v_pk_fma_f32 v[40:41], v[0:1], v[68:69], v[40:41] op_sel_hi:[0,1,1]
	v_pk_fma_f32 v[18:19], v[0:1], v[66:67], v[18:19] op_sel_hi:[0,1,1]
	s_waitcnt lgkmcnt(10)
	v_pk_fma_f32 v[64:65], v[20:21], v[80:81], v[64:65] op_sel_hi:[0,1,1]
	v_pk_fma_f32 v[62:63], v[20:21], v[78:79], v[62:63] op_sel_hi:[0,1,1]
	v_pk_fma_f32 v[40:41], v[20:21], v[76:77], v[40:41] op_sel_hi:[0,1,1]
	v_pk_fma_f32 v[18:19], v[20:21], v[74:75], v[18:19] op_sel_hi:[0,1,1]
	s_waitcnt lgkmcnt(8)
	v_pk_fma_f32 v[64:65], v[52:53], v[88:89], v[64:65] op_sel_hi:[0,1,1]
	v_pk_fma_f32 v[62:63], v[52:53], v[86:87], v[62:63] op_sel_hi:[0,1,1]
	v_pk_fma_f32 v[40:41], v[52:53], v[84:85], v[40:41] op_sel_hi:[0,1,1]
	v_pk_fma_f32 v[18:19], v[52:53], v[82:83], v[18:19] op_sel_hi:[0,1,1]
	s_waitcnt lgkmcnt(7)
	v_pk_fma_f32 v[18:19], v[22:23], v[26:27], v[18:19] op_sel_hi:[0,1,1]
	v_pk_fma_f32 v[20:21], v[22:23], v[28:29], v[40:41] op_sel_hi:[0,1,1]
	s_waitcnt lgkmcnt(6)
	v_pk_fma_f32 v[26:27], v[22:23], v[90:91], v[62:63] op_sel_hi:[0,1,1]
	v_pk_fma_f32 v[22:23], v[22:23], v[92:93], v[64:65] op_sel_hi:[0,1,1]
	s_waitcnt lgkmcnt(5)
	v_pk_fma_f32 v[18:19], v[60:61], v[94:95], v[18:19] op_sel_hi:[0,1,1]
	v_pk_fma_f32 v[20:21], v[60:61], v[96:97], v[20:21] op_sel_hi:[0,1,1]
	s_waitcnt lgkmcnt(4)
	v_pk_fma_f32 v[26:27], v[60:61], v[98:99], v[26:27] op_sel_hi:[0,1,1]
	v_pk_fma_f32 v[22:23], v[60:61], v[100:101], v[22:23] op_sel_hi:[0,1,1]
	s_waitcnt lgkmcnt(3)
	v_pk_fma_f32 v[18:19], v[24:25], v[102:103], v[18:19] op_sel_hi:[0,1,1]
	v_pk_fma_f32 v[20:21], v[24:25], v[104:105], v[20:21] op_sel_hi:[0,1,1]
	s_waitcnt lgkmcnt(2)
	v_pk_fma_f32 v[26:27], v[24:25], v[106:107], v[26:27] op_sel_hi:[0,1,1]
	v_pk_fma_f32 v[22:23], v[24:25], v[108:109], v[22:23] op_sel_hi:[0,1,1]
	s_waitcnt lgkmcnt(1)
	v_pk_fma_f32 v[18:19], v[56:57], v[110:111], v[18:19] op_sel_hi:[0,1,1]
	v_pk_fma_f32 v[24:25], v[56:57], v[112:113], v[20:21] op_sel_hi:[0,1,1]
	s_waitcnt lgkmcnt(0)
	v_pk_fma_f32 v[26:27], v[56:57], v[114:115], v[26:27] op_sel_hi:[0,1,1]
	v_pk_fma_f32 v[38:39], v[56:57], v[116:117], v[22:23] op_sel_hi:[0,1,1]
	v_mov_b32_e32 v20, v1
	v_mov_b32_e32 v21, v1
	v_mov_b32_e32 v22, v1
	v_mov_b32_e32 v23, v1
	v_mov_b32_e32 v28, v1
	v_mov_b32_e32 v29, v1
	v_mov_b32_e32 v40, v1
	v_mov_b32_e32 v41, v1
	v_mov_b32_dpp v20, v18 quad_perm:[1,0,3,2] row_mask:0xf bank_mask:0xf
	v_mov_b32_dpp v21, v19 quad_perm:[1,0,3,2] row_mask:0xf bank_mask:0xf
	v_mov_b32_dpp v22, v24 quad_perm:[1,0,3,2] row_mask:0xf bank_mask:0xf
	v_mov_b32_dpp v23, v25 quad_perm:[1,0,3,2] row_mask:0xf bank_mask:0xf
	v_mov_b32_dpp v28, v26 quad_perm:[1,0,3,2] row_mask:0xf bank_mask:0xf
	v_mov_b32_dpp v29, v27 quad_perm:[1,0,3,2] row_mask:0xf bank_mask:0xf
	v_mov_b32_dpp v40, v38 quad_perm:[1,0,3,2] row_mask:0xf bank_mask:0xf
	v_mov_b32_dpp v41, v39 quad_perm:[1,0,3,2] row_mask:0xf bank_mask:0xf
	v_pk_add_f32 v[18:19], v[18:19], v[20:21]
	v_mov_b32_e32 v20, v1
	v_mov_b32_e32 v21, v1
	v_pk_add_f32 v[22:23], v[24:25], v[22:23]
	v_mov_b32_e32 v24, v1
	v_mov_b32_e32 v25, v1
	v_pk_add_f32 v[26:27], v[26:27], v[28:29]
	v_mov_b32_e32 v28, v1
	v_mov_b32_e32 v29, v1
	v_pk_add_f32 v[38:39], v[38:39], v[40:41]
	v_mov_b32_e32 v40, v1
	v_mov_b32_e32 v41, v1
	v_mov_b32_dpp v20, v18 quad_perm:[2,3,0,1] row_mask:0xf bank_mask:0xf
	v_mov_b32_dpp v21, v19 quad_perm:[2,3,0,1] row_mask:0xf bank_mask:0xf
	v_mov_b32_dpp v24, v22 quad_perm:[2,3,0,1] row_mask:0xf bank_mask:0xf
	v_mov_b32_dpp v25, v23 quad_perm:[2,3,0,1] row_mask:0xf bank_mask:0xf
	v_mov_b32_dpp v28, v26 quad_perm:[2,3,0,1] row_mask:0xf bank_mask:0xf
	v_mov_b32_dpp v29, v27 quad_perm:[2,3,0,1] row_mask:0xf bank_mask:0xf
	v_mov_b32_dpp v40, v38 quad_perm:[2,3,0,1] row_mask:0xf bank_mask:0xf
	v_mov_b32_dpp v41, v39 quad_perm:[2,3,0,1] row_mask:0xf bank_mask:0xf
	s_and_saveexec_b64 s[6:7], s[0:1]
	s_cbranch_execz .Lrs_odd_bot
	v_pk_add_f32 v[18:19], v[18:19], v[20:21]
	v_pk_add_f32 v[20:21], v[22:23], v[24:25]
	v_pk_add_f32 v[10:11], v[10:11], v[18:19]
	v_add_co_u32_e32 v18, vcc, 0xbe00000, v50
	v_pk_add_f32 v[26:27], v[26:27], v[28:29]
	v_pk_add_f32 v[28:29], v[38:39], v[40:41]
	v_pk_add_f32 v[12:13], v[12:13], v[20:21]
	v_add_u32_e32 v0, s8, v53
	v_addc_co_u32_e32 v19, vcc, 0, v51, vcc
	v_pk_add_f32 v[16:17], v[16:17], v[28:29]
	v_pk_add_f32 v[14:15], v[14:15], v[26:27]
	ds_write_b128 v0, v[10:13] offset:40960
	ds_write_b128 v0, v[14:17] offset:40976
	global_store_dwordx4 v[18:19], v[10:13], off
	global_store_dwordx4 v[18:19], v[14:17], off offset:16
	s_branch .Lrs_odd_bot
